# cooperative grid sync after prep: arrival only, then per-XCC census ticket (ticket 0 writes that L2 back); barrier 1 uses the two-level protocol too
# baseline (speedup 1.0000x reference)
.LBB0_287:
	v_lshrrev_b32_e32 v1, 20, v0
	v_lshrrev_b32_e32 v0, 10, v0
	v_or_b32_e32 v0, v0, v1
	s_movk_i32 s0, 0x3ff
	v_and_or_b32 v0, v0, s0, v222
	v_cmp_eq_u32_e32 vcc, 0, v0
	s_barrier
	s_and_saveexec_b64 s[0:1], vcc
	s_cbranch_execz .LBB0_297
	s_waitcnt vmcnt(0)
	s_load_dwordx2 s[4:5], s[30:31], 0x58
	v_mov_b32_e32 v2, 0
	s_mov_b64 s[6:7], exec
	v_mbcnt_lo_u32_b32 v1, s6, 0
	v_mbcnt_hi_u32_b32 v1, s7, v1
	s_waitcnt lgkmcnt(0)
	global_load_dword v0, v2, s[4:5] offset:40
	v_cmp_eq_u32_e32 vcc, 0, v1
	s_and_saveexec_b64 s[8:9], vcc
	s_cbranch_execz .LBB0_290
	s_bcnt1_i32_b64 s3, s[6:7]
	v_mov_b32_e32 v3, s3
	global_atomic_add v3, v2, v3, s[4:5] offset:32 sc0

.LBB0_296:
	s_mov_b64 exec, 1
	s_getreg_b32 s6, hwreg(HW_REG_XCC_ID)
	s_and_b32 s6, s6, 15
	s_nop 0
	v_writelane_b32 v255, s6, 51
	s_lshl_b32 s7, s6, 2
	s_add_i32 s7, s7, 0xc0
	v_mov_b32_e32 v1, s7
	v_mov_b32_e32 v2, 1
	v_mov_b32_e32 v0, 0
	global_atomic_add v3, v1, v2, s[44:45] sc0
	s_waitcnt vmcnt(0)
	v_readfirstlane_b32 s7, v3
	s_cmp_lg_u32 s7, 0
	s_cbranch_scc1 .Lhbs_nf
	buffer_wbl2 sc1
	s_waitcnt vmcnt(0)
	global_atomic_add v0, v2, s[44:45] offset:384
.Lhbs_nf:
	s_mov_b32 s8, 0
.Lhbs_cen:
	v_mov_b32_e32 v1, 0xc0
	global_load_dwordx4 v[4:7], v1, s[44:45] sc1
	global_load_dwordx4 v[8:11], v1, s[44:45] offset:16 sc1
	s_waitcnt vmcnt(0)
	s_mov_b32 s6, 0
	s_mov_b32 s9, 0
	v_readfirstlane_b32 s7, v4
	s_add_i32 s9, s9, s7
	s_cmp_lg_u32 s7, 0
	s_cselect_b32 s7, 1, 0
	s_add_i32 s6, s6, s7
	v_readfirstlane_b32 s7, v5
	s_add_i32 s9, s9, s7
	s_cmp_lg_u32 s7, 0
	s_cselect_b32 s7, 1, 0
	s_add_i32 s6, s6, s7
	v_readfirstlane_b32 s7, v6
	s_add_i32 s9, s9, s7
	s_cmp_lg_u32 s7, 0
	s_cselect_b32 s7, 1, 0
	s_add_i32 s6, s6, s7
	v_readfirstlane_b32 s7, v7
	s_add_i32 s9, s9, s7
	s_cmp_lg_u32 s7, 0
	s_cselect_b32 s7, 1, 0
	s_add_i32 s6, s6, s7
	v_readfirstlane_b32 s7, v8
	s_add_i32 s9, s9, s7
	s_cmp_lg_u32 s7, 0
	s_cselect_b32 s7, 1, 0
	s_add_i32 s6, s6, s7
	v_readfirstlane_b32 s7, v9
	s_add_i32 s9, s9, s7
	s_cmp_lg_u32 s7, 0
	s_cselect_b32 s7, 1, 0
	s_add_i32 s6, s6, s7
	v_readfirstlane_b32 s7, v10
	s_add_i32 s9, s9, s7
	s_cmp_lg_u32 s7, 0
	s_cselect_b32 s7, 1, 0
	s_add_i32 s6, s6, s7
	v_readfirstlane_b32 s7, v11
	s_add_i32 s9, s9, s7
	s_cmp_lg_u32 s7, 0
	s_cselect_b32 s7, 1, 0
	s_add_i32 s6, s6, s7
	s_cmp_eq_u32 s9, s95
	s_cbranch_scc1 .Lhbs_cd
	s_sleep 3
	s_add_i32 s8, s8, 1
	s_cmp_lt_u32 s8, 0x20000
	s_cbranch_scc1 .Lhbs_cen
.Lhbs_cd:
	s_nop 0
	v_writelane_b32 v255, s6, 53
	v_readlane_b32 s7, v255, 51
	s_lshl_b32 s7, s7, 2
	s_add_i32 s7, s7, 0xc0
	v_mov_b32_e32 v1, s7
	global_load_dword v2, v1, s[44:45] sc1
	s_waitcnt vmcnt(0)
	v_readfirstlane_b32 s7, v2
	s_nop 0
	v_writelane_b32 v255, s7, 52
	s_mov_b32 s8, 0
.Lhbs_poll:
	global_load_dword v1, v0, s[44:45] offset:384 sc1
	s_waitcnt vmcnt(0)
	v_cmp_gt_u32_e32 vcc, s6, v1
	s_cbranch_vccz .Lhbs_done
	s_sleep 3
	s_add_i32 s8, s8, 1
	s_cmp_lt_u32 s8, 0x20000
	s_cbranch_scc1 .Lhbs_poll

.LBB0_307:
.LBB0_309:
	s_mov_b32 s4, 1
	v_mov_b32_e32 v0, 0
	v_readlane_b32 s5, v255, 51
	s_lshl_b32 s5, s5, 6
	s_add_i32 s5, s5, 0x200
	v_mov_b32_e32 v1, s5
	v_mov_b32_e32 v2, 1
	global_atomic_add v3, v1, v2, s[44:45] sc0
	v_readlane_b32 s6, v255, 52
	s_mul_i32 s6, s6, s4
	s_waitcnt vmcnt(0)
	v_readfirstlane_b32 s7, v3
	s_add_i32 s7, s7, 1
	s_cmp_lg_u32 s7, s6
	s_cbranch_scc1 .Lhb0_nl
	buffer_wbl2 sc1
	s_waitcnt vmcnt(0)
	global_atomic_add v0, v2, s[44:45] offset:256

.Lhb0_poll:
	global_load_dword v1, v0, s[44:45] offset:256 sc1
	s_waitcnt vmcnt(0)
	v_cmp_gt_u32_e32 vcc, s4, v1
	s_cbranch_vccz .Lhb0_done
	s_sleep 3
	s_add_i32 s5, s5, 1
	s_cmp_lt_u32 s5, 0x20000
	s_cbranch_scc1 .Lhb0_poll

.LBB0_690:
	s_waitcnt vmcnt(0) lgkmcnt(0)
	s_waitcnt lgkmcnt(0)
	s_barrier
	s_mov_b64 s[2:3], exec
	v_readlane_b32 s4, v254, 58
	v_readlane_b32 s5, v254, 59
	s_and_b64 s[4:5], s[2:3], s[4:5]
	v_readlane_b32 s33, v254, 30
	v_readlane_b32 s36, v254, 31
	s_mov_b64 exec, s[4:5]
	s_cbranch_execz .LBB0_696
	s_mov_b64 s[4:5], exec
	v_readlane_b32 s4, v255, 31
	s_add_i32 s4, s4, 1
	v_readlane_b32 s5, v255, 51
	s_lshl_b32 s5, s5, 6
	s_add_i32 s5, s5, 0x200
	v_mov_b32_e32 v1, s5
	v_mov_b32_e32 v2, 1
	global_atomic_add v3, v1, v2, s[44:45] sc0
	v_readlane_b32 s6, v255, 52
	s_mul_i32 s6, s6, s4
	s_waitcnt vmcnt(0)
	v_readfirstlane_b32 s7, v3
	s_add_i32 s7, s7, 1
	s_cmp_lg_u32 s7, s6
	s_cbranch_scc1 .Lhb1_nl
	buffer_wbl2 sc1
	s_waitcnt vmcnt(0)
	global_atomic_add v211, v2, s[44:45] offset:256

.LBB0_991:
	s_waitcnt vmcnt(0) lgkmcnt(0)
	s_waitcnt vmcnt(63) expcnt(7) lgkmcnt(15)
	s_barrier
	s_mov_b64 s[2:3], exec
	v_readlane_b32 s4, v254, 58
	v_readlane_b32 s5, v254, 59
	v_readlane_b32 s12, v255, 33
	s_and_b64 s[4:5], s[2:3], s[4:5]
	v_readlane_b32 s13, v255, 34
	s_mov_b64 exec, s[4:5]
	s_cbranch_execz .LBB0_997
	s_mov_b64 s[4:5], exec
	v_readlane_b32 s4, v255, 31
	s_add_i32 s4, s4, 2
	v_readlane_b32 s5, v255, 51
	s_lshl_b32 s5, s5, 6
	s_add_i32 s5, s5, 0x200
	v_mov_b32_e32 v1, s5
	v_mov_b32_e32 v2, 1
	global_atomic_add v3, v1, v2, s[44:45] sc0
	v_readlane_b32 s6, v255, 52
	s_mul_i32 s6, s6, s4
	s_waitcnt vmcnt(0)
	v_readfirstlane_b32 s7, v3
	s_add_i32 s7, s7, 1
	s_cmp_lg_u32 s7, s6
	s_cbranch_scc1 .Lhb2_nl
	buffer_wbl2 sc1
	s_waitcnt vmcnt(0)
	global_atomic_add v211, v2, s[44:45] offset:256

.LBB0_1065:
	s_waitcnt vmcnt(0) lgkmcnt(0)
	s_barrier
	s_mov_b64 s[2:3], exec
	v_readlane_b32 s4, v254, 58
	v_readlane_b32 s5, v254, 59
	s_and_b64 s[4:5], s[2:3], s[4:5]
	s_mov_b64 exec, s[4:5]
	s_cbranch_execz .LBB0_1071
	s_mov_b64 s[4:5], exec
	v_readlane_b32 s4, v255, 31
	s_add_i32 s4, s4, 3
	v_readlane_b32 s5, v255, 51
	s_lshl_b32 s5, s5, 6
	s_add_i32 s5, s5, 0x200
	v_mov_b32_e32 v1, s5
	v_mov_b32_e32 v2, 1
	global_atomic_add v3, v1, v2, s[44:45] sc0
	v_readlane_b32 s10, v255, 52
	s_mul_i32 s10, s10, s4
	s_waitcnt vmcnt(0)
	v_readfirstlane_b32 s11, v3
	s_add_i32 s11, s11, 1
	s_cmp_lg_u32 s11, s10
	s_cbranch_scc1 .Lhb3_nl
	buffer_wbl2 sc1
	s_waitcnt vmcnt(0)
	global_atomic_add v211, v2, s[44:45] offset:256

.LBB0_1078:
	s_or_b64 exec, exec, s[2:3]
	s_waitcnt vmcnt(0) lgkmcnt(0)
	s_barrier
	s_mov_b64 s[2:3], exec
	v_readlane_b32 s4, v254, 58
	v_readlane_b32 s5, v254, 59
	s_and_b64 s[4:5], s[2:3], s[4:5]
	s_mov_b64 exec, s[4:5]
	s_cbranch_execz .LBB0_1084
	s_mov_b64 s[4:5], exec
	v_readlane_b32 s4, v255, 31
	s_add_i32 s4, s4, 4
	v_readlane_b32 s5, v255, 51
	s_lshl_b32 s5, s5, 6
	s_add_i32 s5, s5, 0x200
	v_mov_b32_e32 v1, s5
	v_mov_b32_e32 v2, 1
	global_atomic_add v3, v1, v2, s[44:45] sc0
	v_readlane_b32 s10, v255, 52
	s_mul_i32 s10, s10, s4
	s_waitcnt vmcnt(0)
	v_readfirstlane_b32 s11, v3
	s_add_i32 s11, s11, 1
	s_cmp_lg_u32 s11, s10
	s_cbranch_scc1 .Lhb4_nl
	buffer_wbl2 sc1
	s_waitcnt vmcnt(0)
	global_atomic_add v211, v2, s[44:45] offset:256

.LBB0_1136:
	s_waitcnt vmcnt(0) lgkmcnt(0)
	s_barrier
	s_mov_b64 s[2:3], exec
	v_readlane_b32 s4, v254, 58
	v_readlane_b32 s5, v254, 59
	s_and_b64 s[4:5], s[2:3], s[4:5]
	s_mov_b64 exec, s[4:5]
	s_cbranch_execz .LBB0_1142
	s_mov_b64 s[4:5], exec
	v_readlane_b32 s4, v255, 31
	s_add_i32 s4, s4, 5
	v_readlane_b32 s5, v255, 51
	s_lshl_b32 s5, s5, 6
	s_add_i32 s5, s5, 0x200
	v_mov_b32_e32 v1, s5
	v_mov_b32_e32 v2, 1
	global_atomic_add v3, v1, v2, s[44:45] sc0
	v_readlane_b32 s10, v255, 52
	s_mul_i32 s10, s10, s4
	s_waitcnt vmcnt(0)
	v_readfirstlane_b32 s11, v3
	s_add_i32 s11, s11, 1
	s_cmp_lg_u32 s11, s10
	s_cbranch_scc1 .Lhb5_nl
	buffer_wbl2 sc1
	s_waitcnt vmcnt(0)
	global_atomic_add v211, v2, s[44:45] offset:256

.LBB0_1178:
	s_waitcnt vmcnt(0) lgkmcnt(0)
	v_readlane_b32 s2, v255, 31
	s_add_i32 s9, s2, 6
	s_barrier
	s_mov_b64 s[2:3], exec
	v_readlane_b32 s4, v254, 58
	v_readlane_b32 s5, v254, 59
	s_and_b64 s[4:5], s[2:3], s[4:5]
	s_movk_i32 s39, 0x1200
	s_mov_b32 s40, 0x5040100
	s_movk_i32 s41, 0x301
	s_mov_b64 s[54:55], 0xf32e600
	s_mov_b64 exec, s[4:5]
	s_cbranch_execz .LBB0_1184
	s_mov_b64 s[4:5], exec
	s_mov_b32 s4, s9
	v_readlane_b32 s5, v255, 51
	s_lshl_b32 s5, s5, 6
	s_add_i32 s5, s5, 0x200
	v_mov_b32_e32 v1, s5
	v_mov_b32_e32 v2, 1
	global_atomic_add v3, v1, v2, s[44:45] sc0
	v_readlane_b32 s6, v255, 52
	s_mul_i32 s6, s6, s4
	s_waitcnt vmcnt(0)
	v_readfirstlane_b32 s7, v3
	s_add_i32 s7, s7, 1
	s_cmp_lg_u32 s7, s6
	s_cbranch_scc1 .Lhb6_nl
	buffer_wbl2 sc1
	s_waitcnt vmcnt(0)
	global_atomic_add v211, v2, s[44:45] offset:256

.LBB0_1193:
	s_mov_b64 s[4:5], exec
	s_mov_b32 s4, s9
	v_readlane_b32 s5, v255, 51
	s_lshl_b32 s5, s5, 6
	s_add_i32 s5, s5, 0x200
	v_mov_b32_e32 v1, s5
	v_mov_b32_e32 v2, 1
	global_atomic_add v3, v1, v2, s[44:45] sc0
	v_readlane_b32 s6, v255, 52
	s_mul_i32 s6, s6, s4
	s_waitcnt vmcnt(0)
	v_readfirstlane_b32 s7, v3
	s_add_i32 s7, s7, 1
	s_cmp_lg_u32 s7, s6
	s_cbranch_scc1 .Lhb7_nl
	buffer_wbl2 sc1
	s_waitcnt vmcnt(0)
	global_atomic_add v211, v2, s[44:45] offset:256
